# MLA loop: cross-half max exchange + vcc compare moved to rare rescale path; row-sum l kept as per-lane partials, combined once at loop exit (-7 VALU/tile)
# baseline (speedup 1.0000x reference)
; #define SBAR() __builtin_amdgcn_sched_barrier(0)
; #define SLOAD(i, j) do { const long kr_ = KROW(j); sr_[i].vs0 = ld8(Vp + (kr_ + sr) * ldv + sc); sr_[i].ks0 = ld8(Kp + (kr_ + sr) * ldk + sc); \
;     if (DQK == 96) sr_[i].ks1 = ld8(Kp + (kr_ + sr2) * ldk + sc2); } while (0)
; #define BIAS(P0, P1, j) do { if (MODE == 1) { SBAR(); if ((j) >= nA) na_bias(P0, P1, na, rs0 + (j) - nA, hi); SBAR(); } } while (0)
; template <int DQK> __device__ __forceinline__ void partialSM(f32x16& p0, f32x16& p1, float& m_reg, float& mn, float& alpha) {
;   constexpr float SCALE = (DQK == 96) ? 0.10206207261596577f : 0.125f;
;   constexpr float C = SCALE * 1.4426950408889634f;
;   float pmax = p0[0];
; #pragma unroll
;   for (int r = 1; r < 16; ++r) pmax = fmaxf(pmax, p0[r]);
; #pragma unroll
;   for (int r = 0; r < 16; ++r) pmax = fmaxf(pmax, p1[r]);
;   { auto rr = __builtin_amdgcn_permlane32_swap(__float_as_uint(pmax), __float_as_uint(pmax), false, false);
;     pmax = fmaxf(__uint_as_float(rr[0]), __uint_as_float(rr[1])); }
;   if (__builtin_expect(__all(pmax - m_reg <= THR / SCALE), 1)) { mn = m_reg; alpha = 1.f; }
;   else { mn = fmaxf(m_reg, pmax); alpha = __builtin_amdgcn_exp2f((m_reg - mn) * C); m_reg = mn; }
; template <int DQK, int MODE, int ldq, int ldk, int ldv> ...
;     ...
;   for (int j = 1; j + 1 < NT; j += 2) {
;     SBAR(); qkt<DQK>(pB0, pB1, K_lds + SHM_K, qr, r32, hi);
;     finishSM(pA0, pA1, alA, l_reg, pa0, pa1, pa2, pa3); SBAR();
;     SLOAD(SO, j + 2); SBAR();
;     pv_d0(o, vb0, pa0, pa1, pa2, pa3); BIAS(pB0, pB1, j); partialSM<DQK>(pB0, pB1, m_reg, mnB, alB);
.LBB0_300:
	s_add_i32 s25, s11, -3
	s_cmp_lg_u32 s32, 0
	s_cbranch_scc1 .Lmy_h1B
	ds_read_b128 v[32:35], v148 offset:49152
	ds_read_b128 v[36:39], v148 offset:57344
	ds_read_b128 v[164:167], v152 offset:49152
	ds_read_b128 v[168:171], v152 offset:57344
	s_waitcnt lgkmcnt(3)
	v_mfma_f32_32x32x16_bf16 v[48:63], v[32:35], v[84:87], v[210:225]
	s_waitcnt lgkmcnt(2)
	v_mfma_f32_32x32x16_bf16 v[32:47], v[36:39], v[84:87], v[210:225]
	s_waitcnt lgkmcnt(1)
	v_mfma_f32_32x32x16_bf16 v[48:63], v[164:167], v[80:83], v[48:63]
	s_waitcnt lgkmcnt(0)
	v_mfma_f32_32x32x16_bf16 v[32:47], v[168:171], v[80:83], v[32:47]
	ds_read_b128 v[164:167], v151 offset:49152
	ds_read_b128 v[168:171], v151 offset:57344
	s_waitcnt lgkmcnt(1)
	v_mfma_f32_32x32x16_bf16 v[48:63], v[164:167], v[76:79], v[48:63]
	s_waitcnt lgkmcnt(0)
	v_mfma_f32_32x32x16_bf16 v[32:47], v[168:171], v[76:79], v[32:47]
	ds_read_b128 v[164:167], v149 offset:49152
	ds_read_b128 v[168:171], v149 offset:57344
	s_waitcnt lgkmcnt(1)
	v_mfma_f32_32x32x16_bf16 v[48:63], v[164:167], v[72:75], v[48:63]
	s_waitcnt lgkmcnt(0)
	v_mfma_f32_32x32x16_bf16 v[32:47], v[168:171], v[72:75], v[32:47]
	ds_read_b128 v[164:167], v150 offset:49152
	ds_read_b128 v[168:171], v150 offset:57344
	s_waitcnt lgkmcnt(1)
	v_mfma_f32_32x32x16_bf16 v[48:63], v[164:167], v[68:71], v[48:63]
	s_waitcnt lgkmcnt(0)
	v_mfma_f32_32x32x16_bf16 v[32:47], v[168:171], v[68:71], v[32:47]
	ds_read_b128 v[164:167], v153 offset:49152
	ds_read_b128 v[168:171], v153 offset:57344
	s_waitcnt vmcnt(0)
	ds_write_b128 v146, v[88:91] offset:32768
	ds_write_b128 v147, v[96:99] offset:32768
	ds_write_b128 v145, v[92:95] offset:16384
	s_waitcnt lgkmcnt(4)
	v_mfma_f32_32x32x16_bf16 v[48:63], v[164:167], v[64:67], v[48:63]
	s_waitcnt lgkmcnt(3)
	v_mfma_f32_32x32x16_bf16 v[32:47], v[168:171], v[64:67], v[32:47]
	ds_read_b64_tr_b16 v[184:185], v144 offset:0
	ds_read_b64_tr_b16 v[186:187], v144 offset:0x800
	ds_read_b64_tr_b16 v[188:189], v144 offset:0x1000
	ds_read_b64_tr_b16 v[190:191], v144 offset:0x1800
	ds_read_b64_tr_b16 v[192:193], v144 offset:0x2000
	ds_read_b64_tr_b16 v[194:195], v144 offset:0x2800
	ds_read_b64_tr_b16 v[196:197], v144 offset:0x3000
	ds_read_b64_tr_b16 v[198:199], v144 offset:0x3800
	v_mov_b32_e32 v117, v114
	v_mov_b32_e32 v157, v115
	v_mov_b32_e32 v164, v112
	v_add_f32_e32 v112, 0, v126
	v_add_f32_e32 v112, v160, v112
	v_add_f32_e32 v112, v127, v112
	v_add_f32_e32 v112, v161, v112
	v_add_f32_e32 v112, v158, v112
	v_add_f32_e32 v112, v162, v112
	v_add_f32_e32 v112, v159, v112
	v_add_f32_e32 v112, v163, v112
	v_add_f32_e32 v112, v118, v112
	v_add_f32_e32 v112, v121, v112
	v_add_f32_e32 v112, v119, v112
	v_add_f32_e32 v112, v122, v112
	v_add_f32_e32 v112, v120, v112
	v_add_f32_e32 v112, v123, v112
	v_add_f32_e32 v112, v124, v112
	v_mov_b32_e32 v165, v113
	v_add_f32_e32 v112, v125, v112
	v_add_f32_e32 v112, v117, v112
	v_add_f32_e32 v112, v157, v112
	v_add_f32_e32 v112, v164, v112
	v_add_f32_e32 v112, v165, v112
	v_add_f32_e32 v112, v108, v112
	v_add_f32_e32 v112, v109, v112
	v_add_f32_e32 v112, v104, v112
	v_add_f32_e32 v112, v105, v112
	v_add_f32_e32 v112, v102, v112
	v_add_f32_e32 v112, v103, v112
	v_add_f32_e32 v112, v110, v112
	v_add_f32_e32 v112, v111, v112
	v_add_f32_e32 v112, v106, v112
	v_add_f32_e32 v112, v107, v112
	v_add_f32_e32 v112, v100, v112
	v_add_f32_e32 v155, v101, v112
	v_cvt_pk_bf16_f32 v200, v126, v160
	v_cvt_pk_bf16_f32 v201, v127, v161
	v_cvt_pk_bf16_f32 v202, v158, v162
	v_cvt_pk_bf16_f32 v203, v159, v163
	v_cvt_pk_bf16_f32 v226, v118, v121
	v_cvt_pk_bf16_f32 v227, v119, v122
	v_cvt_pk_bf16_f32 v228, v120, v123
	v_cvt_pk_bf16_f32 v229, v124, v125
	v_cvt_pk_bf16_f32 v230, v117, v157
	v_cvt_pk_bf16_f32 v231, v164, v165
	v_cvt_pk_bf16_f32 v232, v108, v109
	v_cvt_pk_bf16_f32 v233, v104, v105
	v_cvt_pk_bf16_f32 v136, v102, v103
	v_cvt_pk_bf16_f32 v137, v110, v111
	v_cvt_pk_bf16_f32 v138, v106, v107
	v_cvt_pk_bf16_f32 v139, v100, v101
	s_lshl_b32 s0, s11, 6
	s_cmpk_lt_u32 s25, 0x7e
	s_cselect_b32 s1, s10, s24
	s_add_i32 s1, s1, s0
	s_addk_i32 s1, 0xffc0
	s_mul_i32 s1, s1, 0x300
	s_add_u32 s12, s18, s1
	s_addc_u32 s13, s19, 0
	s_cmpk_lt_u32 s25, 0x7f
	s_cselect_b32 s98, s10, s24
	s_add_i32 s98, s98, s0
	s_addk_i32 s98, 0xff80
	s_lshl_b32 s98, s98, 9
	s_add_u32 s98, s20, s98
	s_addc_u32 s99, s21, 0
	global_load_dwordx4 v[100:103], v134, s[12:13]
	global_load_dwordx4 v[108:111], v135, s[98:99]
	global_load_dwordx4 v[104:107], v238, s[12:13] offset:128
	s_waitcnt lgkmcnt(0)
	s_nop 0
	v_mfma_f32_32x32x16_bf16 v[0:15], v[200:203], v[184:187], v[0:15]
	ds_read_b64_tr_b16 v[184:185], v144 offset:0x200
	ds_read_b64_tr_b16 v[186:187], v144 offset:0xa00
	v_max_f32_e32 v112, v48, v49
	v_max3_f32 v112, v112, v50, v51
	v_max3_f32 v112, v112, v52, v53
	v_max3_f32 v112, v112, v54, v55
	v_max3_f32 v112, v112, v56, v57
	v_mfma_f32_32x32x16_bf16 v[0:15], v[226:229], v[188:191], v[0:15]
	ds_read_b64_tr_b16 v[188:189], v144 offset:0x1200
	ds_read_b64_tr_b16 v[190:191], v144 offset:0x1a00
	v_max3_f32 v112, v112, v58, v59
	v_max3_f32 v112, v112, v60, v61
	v_max3_f32 v112, v112, v62, v63
	v_max3_f32 v112, v112, v32, v33
	v_max3_f32 v112, v112, v34, v35
	v_mfma_f32_32x32x16_bf16 v[0:15], v[230:233], v[192:195], v[0:15]
	ds_read_b64_tr_b16 v[192:193], v144 offset:0x2200
	ds_read_b64_tr_b16 v[194:195], v144 offset:0x2a00
	v_max3_f32 v112, v112, v36, v37
	v_max3_f32 v112, v112, v38, v39
	v_max3_f32 v112, v112, v40, v41
	v_max3_f32 v112, v112, v42, v43
	v_max3_f32 v112, v112, v44, v45
	v_mfma_f32_32x32x16_bf16 v[0:15], v[136:139], v[196:199], v[0:15]
	ds_read_b64_tr_b16 v[196:197], v144 offset:0x3200
	ds_read_b64_tr_b16 v[198:199], v144 offset:0x3a00
	v_max3_f32 v112, v112, v46, v47
	v_cmp_ge_f32_e32 vcc, s80, v112
	s_cmp_eq_u64 vcc, exec
	s_cbranch_scc0 .Lmy_rare_a1
	v_mov_b32_e32 v157, 1.0
	s_mov_b64 vcc, 0
; #define SBAR() __builtin_amdgcn_sched_barrier(0)
; #define SWRITE(b, i) do { *(bf16x8*)(V_lds + (b) * SHM_V + vst0) = sr_[i].vs0; *(bf16x8*)(K_lds + (b) * SHM_K + kst0) = sr_[i].ks0; \
;     if (DQK == 96) *(bf16x8*)(K_lds + (b) * SHM_K + kst1) = sr_[i].ks1; } while (0)
; #define RESC(a) do { if (__any((a) < 1.f)) { if (hi == 0) al_l[r32] = (a); asm volatile("s_waitcnt lgkmcnt(0)" ::: "memory"); \
;     _Pragma("unroll") for (int d = 0; d < 2; ++d) _Pragma("unroll") for (int r = 0; r < 16; ++r) o[d][r] *= al_l[crow(r, hi)]; } } while (0)
; template <int DQK> __device__ __forceinline__ void partialSM(f32x16& p0, f32x16& p1, float& m_reg, float& mn, float& alpha) {
;     ...
;   for (int r = 0; r < 16; ++r) p0[r] = __builtin_amdgcn_exp2f(p0[r]);
; }
; __device__ __forceinline__ void finishSM(f32x16& p0, f32x16& p1, float alpha, float& l_reg, bf16x8& pa0, bf16x8& pa1, bf16x8& pa2, bf16x8& pa3) {
; #pragma unroll
;   for (int r = 0; r < 16; ++r) p1[r] = __builtin_amdgcn_exp2f(p1[r]);
;   float ps = 0;
; #pragma unroll
;   for (int r = 0; r < 16; ++r) ps += p0[r];
; #pragma unroll
;   for (int r = 0; r < 16; ++r) ps += p1[r];
;   { auto rr = __builtin_amdgcn_permlane32_swap(__float_as_uint(ps), __float_as_uint(ps), false, false);
;     ps = __uint_as_float(rr[0]) + __uint_as_float(rr[1]); }
;   l_reg = l_reg * alpha + ps;
;     ...
;   PK4(p0, 0, pa0); PK4(p0, 8, pa1); PK4(p1, 0, pa2); PK4(p1, 8, pa3);
; template <int DQK, int MODE, int ldq, int ldk, int ldv> ...
;     ...
;     __syncthreads(); SWRITE(0, SE);
;     RESC(alB); __syncthreads();
;     SBAR(); qkt<DQK>(pA0, pA1, K_lds, qr, r32, hi);
;     finishSM(pB0, pB1, alB, l_reg, pa0, pa1, pa2, pa3); SBAR();
.Lmy_join_a1:
	s_waitcnt lgkmcnt(0)
	v_mfma_f32_32x32x16_bf16 v[16:31], v[200:203], v[184:187], v[16:31]
	v_exp_f32_e32 v112, v48
	v_exp_f32_e32 v127, v49
	v_exp_f32_e32 v113, v50
	v_exp_f32_e32 v126, v51
	v_exp_f32_e32 v114, v52
	v_exp_f32_e32 v125, v53
	v_exp_f32_e32 v115, v54
	v_exp_f32_e32 v124, v55
	v_mfma_f32_32x32x16_bf16 v[16:31], v[226:229], v[188:191], v[16:31]
	v_exp_f32_e32 v116, v56
	v_exp_f32_e32 v123, v57
	v_exp_f32_e32 v117, v58
	v_exp_f32_e32 v122, v59
	v_exp_f32_e32 v118, v60
	v_exp_f32_e32 v121, v61
	v_exp_f32_e32 v119, v62
	v_exp_f32_e32 v120, v63
	v_mfma_f32_32x32x16_bf16 v[16:31], v[230:233], v[192:195], v[16:31]
	v_exp_f32_e32 v164, v42
	v_exp_f32_e32 v165, v43
	v_exp_f32_e32 v167, v32
	v_exp_f32_e32 v168, v33
	v_exp_f32_e32 v169, v34
	v_exp_f32_e32 v170, v35
	v_exp_f32_e32 v171, v36
	v_exp_f32_e32 v172, v37
	v_mfma_f32_32x32x16_bf16 v[16:31], v[136:139], v[196:199], v[16:31]
	v_exp_f32_e32 v160, v38
	v_exp_f32_e32 v161, v39
	v_exp_f32_e32 v162, v40
	v_exp_f32_e32 v163, v41
	v_exp_f32_e32 v166, v44
	v_exp_f32_e32 v173, v45
	v_exp_f32_e32 v174, v46
	v_exp_f32_e32 v159, v47
	s_cbranch_vccz .LBB0_304
	s_and_saveexec_b64 s[12:13], s[4:5]
	ds_write_b32 v141, v157 offset:128
	s_or_b64 exec, exec, s[12:13]
	s_waitcnt lgkmcnt(0)
	ds_read_b128 v[184:187], v129 offset:224
	ds_read_b128 v[188:191], v129 offset:192
	ds_read_b128 v[192:195], v129 offset:160
	ds_read_b128 v[196:199], v129 offset:128
	s_waitcnt lgkmcnt(3)
	v_pk_mul_f32 v[14:15], v[14:15], v[186:187]
	s_waitcnt lgkmcnt(2)
	v_pk_mul_f32 v[10:11], v[10:11], v[190:191]
	s_waitcnt lgkmcnt(1)
	v_pk_mul_f32 v[6:7], v[6:7], v[194:195]
	s_waitcnt lgkmcnt(0)
	v_pk_mul_f32 v[2:3], v[2:3], v[198:199]
	v_pk_mul_f32 v[12:13], v[12:13], v[184:185]
	v_pk_mul_f32 v[8:9], v[8:9], v[188:189]
	v_pk_mul_f32 v[4:5], v[4:5], v[192:193]
	v_pk_mul_f32 v[0:1], v[0:1], v[196:197]
	v_pk_mul_f32 v[30:31], v[30:31], v[186:187]
	v_pk_mul_f32 v[26:27], v[26:27], v[190:191]
	v_pk_mul_f32 v[22:23], v[22:23], v[194:195]
	v_pk_mul_f32 v[18:19], v[18:19], v[198:199]
	v_pk_mul_f32 v[28:29], v[28:29], v[184:185]
	v_pk_mul_f32 v[24:25], v[24:25], v[188:189]
	v_pk_mul_f32 v[20:21], v[20:21], v[192:193]
	v_pk_mul_f32 v[16:17], v[16:17], v[196:197]
.LBB0_304:
	s_waitcnt lgkmcnt(0)
	s_barrier
	ds_read_b128 v[32:35], v148 offset:32768
	ds_read_b128 v[36:39], v148 offset:40960
	ds_read_b128 v[176:179], v152 offset:32768
	ds_read_b128 v[180:183], v152 offset:40960
	s_waitcnt lgkmcnt(3)
	v_mfma_f32_32x32x16_bf16 v[48:63], v[32:35], v[84:87], v[210:225]
	s_waitcnt lgkmcnt(2)
	v_mfma_f32_32x32x16_bf16 v[32:47], v[36:39], v[84:87], v[210:225]
	s_waitcnt lgkmcnt(1)
	v_mfma_f32_32x32x16_bf16 v[48:63], v[176:179], v[80:83], v[48:63]
	s_waitcnt lgkmcnt(0)
	v_mfma_f32_32x32x16_bf16 v[32:47], v[180:183], v[80:83], v[32:47]
	ds_read_b128 v[176:179], v151 offset:32768
	ds_read_b128 v[180:183], v151 offset:40960
	s_waitcnt lgkmcnt(1)
	v_mfma_f32_32x32x16_bf16 v[48:63], v[176:179], v[76:79], v[48:63]
	s_waitcnt lgkmcnt(0)
	v_mfma_f32_32x32x16_bf16 v[32:47], v[180:183], v[76:79], v[32:47]
	ds_read_b128 v[176:179], v149 offset:32768
	ds_read_b128 v[180:183], v149 offset:40960
	s_waitcnt lgkmcnt(1)
	v_mfma_f32_32x32x16_bf16 v[48:63], v[176:179], v[72:75], v[48:63]
	s_waitcnt lgkmcnt(0)
	v_mfma_f32_32x32x16_bf16 v[32:47], v[180:183], v[72:75], v[32:47]
	ds_read_b128 v[176:179], v150 offset:32768
	ds_read_b128 v[180:183], v150 offset:40960
	s_waitcnt lgkmcnt(1)
	v_mfma_f32_32x32x16_bf16 v[48:63], v[176:179], v[68:71], v[48:63]
	s_waitcnt lgkmcnt(0)
	v_mfma_f32_32x32x16_bf16 v[32:47], v[180:183], v[68:71], v[32:47]
	ds_read_b128 v[176:179], v153 offset:32768
	ds_read_b128 v[180:183], v153 offset:40960
	s_waitcnt vmcnt(0)
	ds_write_b128 v146, v[100:103] offset:49152
	ds_write_b128 v147, v[104:107] offset:49152
	ds_write_b128 v145, v[108:111]
	s_waitcnt lgkmcnt(4)
	v_mfma_f32_32x32x16_bf16 v[48:63], v[176:179], v[64:67], v[48:63]
	s_waitcnt lgkmcnt(3)
	v_mfma_f32_32x32x16_bf16 v[32:47], v[180:183], v[64:67], v[32:47]
	ds_read_b64_tr_b16 v[184:185], v143 offset:0
	ds_read_b64_tr_b16 v[186:187], v143 offset:0x800
	ds_read_b64_tr_b16 v[188:189], v143 offset:0x1000
	ds_read_b64_tr_b16 v[190:191], v143 offset:0x1800
	ds_read_b64_tr_b16 v[192:193], v143 offset:0x2000
	ds_read_b64_tr_b16 v[194:195], v143 offset:0x2800
	ds_read_b64_tr_b16 v[196:197], v143 offset:0x3000
	ds_read_b64_tr_b16 v[198:199], v143 offset:0x3800
	v_mov_b32_e32 v175, v164
	v_add_f32_e32 v164, 0, v112
	v_add_f32_e32 v164, v127, v164
	v_add_f32_e32 v164, v113, v164
	v_add_f32_e32 v164, v126, v164
	v_add_f32_e32 v164, v114, v164
	v_add_f32_e32 v164, v125, v164
	v_add_f32_e32 v164, v115, v164
	v_add_f32_e32 v164, v124, v164
	v_add_f32_e32 v164, v116, v164
	v_add_f32_e32 v164, v123, v164
	v_add_f32_e32 v164, v117, v164
	v_add_f32_e32 v164, v122, v164
	v_add_f32_e32 v164, v118, v164
	v_add_f32_e32 v164, v121, v164
	v_add_f32_e32 v164, v119, v164
	v_add_f32_e32 v164, v120, v164
	v_add_f32_e32 v164, v167, v164
	v_add_f32_e32 v164, v168, v164
	v_add_f32_e32 v164, v169, v164
	v_add_f32_e32 v164, v170, v164
	v_add_f32_e32 v164, v171, v164
	v_add_f32_e32 v164, v172, v164
	v_add_f32_e32 v164, v160, v164
	v_add_f32_e32 v164, v161, v164
	v_add_f32_e32 v164, v162, v164
	v_add_f32_e32 v164, v163, v164
	v_add_f32_e32 v164, v175, v164
	v_cvt_pk_bf16_f32 v200, v112, v127
	v_cvt_pk_bf16_f32 v201, v113, v126
	v_cvt_pk_bf16_f32 v202, v114, v125
	v_cvt_pk_bf16_f32 v203, v115, v124
	v_cvt_pk_bf16_f32 v226, v116, v123
	v_cvt_pk_bf16_f32 v227, v117, v122
	v_mov_b32_e32 v176, v165
	v_cvt_pk_bf16_f32 v228, v118, v121
	v_cvt_pk_bf16_f32 v229, v119, v120
	v_cvt_pk_bf16_f32 v230, v167, v168
	v_cvt_pk_bf16_f32 v231, v169, v170
	v_cvt_pk_bf16_f32 v232, v171, v172
	s_nop 0
	v_add_f32_e32 v164, v176, v164
	v_add_f32_e32 v164, v166, v164
	v_add_f32_e32 v164, v173, v164
	v_add_f32_e32 v164, v174, v164
	v_add_f32_e32 v164, v159, v164
	v_cvt_pk_bf16_f32 v233, v160, v161
	v_cvt_pk_bf16_f32 v136, v162, v163
	v_cvt_pk_bf16_f32 v137, v175, v176
	v_cvt_pk_bf16_f32 v138, v166, v173
	v_cvt_pk_bf16_f32 v139, v174, v159
	s_lshl_b32 s0, s11, 6
	s_cmpk_lt_u32 s25, 0x7e
	s_cselect_b32 s98, s10, s24
	s_add_i32 s98, s98, s0
	s_addk_i32 s98, 0xffc0
	s_lshl_b32 s98, s98, 9
	s_add_u32 s98, s20, s98
	s_addc_u32 s99, s21, 0
	global_load_dwordx4 v[92:95], v135, s[98:99]
	s_cmpk_gt_u32 s25, 0x80
	s_cbranch_scc1 .LBB0_306
	s_cmpk_lt_u32 s25, 0x7d
	s_cselect_b32 s1, s10, s24
	s_add_i32 s1, s1, s0
	s_mul_i32 s1, s1, 0x300
	s_add_u32 s12, s18, s1
	s_addc_u32 s13, s19, 0
	global_load_dwordx4 v[88:91], v134, s[12:13]
	global_load_dwordx4 v[96:99], v238, s[12:13] offset:128
; #define SWRITE(b, i) do { *(bf16x8*)(V_lds + (b) * SHM_V + vst0) = sr_[i].vs0; *(bf16x8*)(K_lds + (b) * SHM_K + kst0) = sr_[i].ks0; \
;     if (DQK == 96) *(bf16x8*)(K_lds + (b) * SHM_K + kst1) = sr_[i].ks1; } while (0)
; #define BIAS(P0, P1, j) do { if (MODE == 1) { SBAR(); if ((j) >= nA) na_bias(P0, P1, na, rs0 + (j) - nA, hi); SBAR(); } } while (0)
; template <int DQK> __device__ __forceinline__ void partialSM(f32x16& p0, f32x16& p1, float& m_reg, float& mn, float& alpha) {
;   constexpr float SCALE = (DQK == 96) ? 0.10206207261596577f : 0.125f;
;   constexpr float C = SCALE * 1.4426950408889634f;
;   float pmax = p0[0];
; #pragma unroll
;   for (int r = 1; r < 16; ++r) pmax = fmaxf(pmax, p0[r]);
; #pragma unroll
;   for (int r = 0; r < 16; ++r) pmax = fmaxf(pmax, p1[r]);
;   { auto rr = __builtin_amdgcn_permlane32_swap(__float_as_uint(pmax), __float_as_uint(pmax), false, false);
;     pmax = fmaxf(__uint_as_float(rr[0]), __uint_as_float(rr[1])); }
;   if (__builtin_expect(__all(pmax - m_reg <= THR / SCALE), 1)) { mn = m_reg; alpha = 1.f; }
;   else { mn = fmaxf(m_reg, pmax); alpha = __builtin_amdgcn_exp2f((m_reg - mn) * C); m_reg = mn; }
;   float mnC = -mn * C;
; #pragma unroll
;   for (int r = 0; r < 16; ++r) p0[r] = fmaf(p0[r], C, mnC);
; #pragma unroll
;   for (int r = 0; r < 16; ++r) p1[r] = fmaf(p1[r], C, mnC);
; #pragma unroll
;   for (int r = 0; r < 16; ++r) p0[r] = __builtin_amdgcn_exp2f(p0[r]);
; }
; __device__ __forceinline__ void finishSM(f32x16& p0, f32x16& p1, float alpha, float& l_reg, bf16x8& pa0, bf16x8& pa1, bf16x8& pa2, bf16x8& pa3) {
; #pragma unroll
;   for (int r = 0; r < 16; ++r) p1[r] = __builtin_amdgcn_exp2f(p1[r]);
;   float ps = 0;
; #pragma unroll
;   for (int r = 0; r < 16; ++r) ps += p0[r];
; #pragma unroll
;   for (int r = 0; r < 16; ++r) ps += p1[r];
;   { auto rr = __builtin_amdgcn_permlane32_swap(__float_as_uint(ps), __float_as_uint(ps), false, false);
;     ps = __uint_as_float(rr[0]) + __uint_as_float(rr[1]); }
;   l_reg = l_reg * alpha + ps;
; template <int DQK, int MODE, int ldq, int ldk, int ldv> ...
;     ...
;     pv_d0(o, vb0 + (int)SHM_V, pa0, pa1, pa2, pa3); BIAS(pA0, pA1, j + 1); partialSM<DQK>(pA0, pA1, m_reg, mnA, alA);
;     __syncthreads(); SWRITE(1, SO);
;     RESC(alA); __syncthreads();
.LBB0_306:
	s_waitcnt lgkmcnt(0)
	s_nop 0
	v_mfma_f32_32x32x16_bf16 v[0:15], v[200:203], v[184:187], v[0:15]
	ds_read_b64_tr_b16 v[184:185], v143 offset:0x200
	ds_read_b64_tr_b16 v[186:187], v143 offset:0xa00
	v_max_f32_e32 v112, v48, v49
	v_max3_f32 v112, v112, v50, v51
	v_max3_f32 v112, v112, v52, v53
	v_max3_f32 v112, v112, v54, v55
	v_max3_f32 v112, v112, v56, v57
	v_mfma_f32_32x32x16_bf16 v[0:15], v[226:229], v[188:191], v[0:15]
	ds_read_b64_tr_b16 v[188:189], v143 offset:0x1200
	ds_read_b64_tr_b16 v[190:191], v143 offset:0x1a00
	v_max3_f32 v112, v112, v58, v59
	v_max3_f32 v112, v112, v60, v61
	v_max3_f32 v112, v112, v62, v63
	v_max3_f32 v112, v112, v32, v33
	v_max3_f32 v112, v112, v34, v35
	v_mfma_f32_32x32x16_bf16 v[0:15], v[230:233], v[192:195], v[0:15]
	ds_read_b64_tr_b16 v[192:193], v143 offset:0x2200
	ds_read_b64_tr_b16 v[194:195], v143 offset:0x2a00
	v_max3_f32 v112, v112, v36, v37
	v_max3_f32 v112, v112, v38, v39
	v_max3_f32 v112, v112, v40, v41
	v_max3_f32 v112, v112, v42, v43
	v_max3_f32 v112, v112, v44, v45
	v_mfma_f32_32x32x16_bf16 v[0:15], v[136:139], v[196:199], v[0:15]
	ds_read_b64_tr_b16 v[196:197], v143 offset:0x3200
	ds_read_b64_tr_b16 v[198:199], v143 offset:0x3a00
	v_max3_f32 v112, v112, v46, v47
	v_cmp_ge_f32_e32 vcc, s80, v112
	s_cmp_eq_u64 vcc, exec
	s_cbranch_scc0 .Lmy_rare_a2
	v_mov_b32_e32 v117, 1.0
	s_mov_b64 vcc, 0
.Lmy_join_a2:
	s_waitcnt lgkmcnt(0)
	v_mfma_f32_32x32x16_bf16 v[16:31], v[200:203], v[184:187], v[16:31]
	v_exp_f32_e32 v126, v48
	v_exp_f32_e32 v160, v49
	v_exp_f32_e32 v127, v50
	v_exp_f32_e32 v161, v51
	v_exp_f32_e32 v158, v52
	v_exp_f32_e32 v162, v53
	v_exp_f32_e32 v159, v54
	v_exp_f32_e32 v163, v55
	v_exp_f32_e32 v118, v56
	v_mfma_f32_32x32x16_bf16 v[16:31], v[226:229], v[188:191], v[16:31]
	v_exp_f32_e32 v121, v57
	v_exp_f32_e32 v119, v58
	v_exp_f32_e32 v122, v59
	v_exp_f32_e32 v120, v60
	v_exp_f32_e32 v123, v61
	v_exp_f32_e32 v124, v62
	v_exp_f32_e32 v125, v63
	v_exp_f32_e32 v114, v32
	v_exp_f32_e32 v115, v33
	v_mfma_f32_32x32x16_bf16 v[16:31], v[230:233], v[192:195], v[16:31]
	v_exp_f32_e32 v112, v34
	v_exp_f32_e32 v113, v35
	v_exp_f32_e32 v108, v36
	v_exp_f32_e32 v109, v37
	v_exp_f32_e32 v104, v38
	v_exp_f32_e32 v105, v39
	v_exp_f32_e32 v102, v40
	v_exp_f32_e32 v103, v41
	v_exp_f32_e32 v110, v42
	v_mfma_f32_32x32x16_bf16 v[16:31], v[136:139], v[196:199], v[16:31]
	v_exp_f32_e32 v111, v43
	v_exp_f32_e32 v106, v44
	v_exp_f32_e32 v107, v45
	v_exp_f32_e32 v101, v47
	v_exp_f32_e32 v100, v46
	v_fmac_f32_e32 v155, v154, v142
	v_fma_f32 v142, v155, v157, v164
	s_cbranch_vccz .LBB0_310
	s_and_saveexec_b64 s[12:13], s[4:5]
	ds_write_b32 v141, v117 offset:128
	s_or_b64 exec, exec, s[12:13]
	s_waitcnt lgkmcnt(0)
	ds_read_b128 v[184:187], v129 offset:224
	ds_read_b128 v[188:191], v129 offset:192
	ds_read_b128 v[192:195], v129 offset:160
	ds_read_b128 v[196:199], v129 offset:128
	s_waitcnt lgkmcnt(3)
	v_pk_mul_f32 v[14:15], v[14:15], v[186:187]
	s_waitcnt lgkmcnt(2)
	v_pk_mul_f32 v[10:11], v[10:11], v[190:191]
	s_waitcnt lgkmcnt(1)
	v_pk_mul_f32 v[6:7], v[6:7], v[194:195]
	s_waitcnt lgkmcnt(0)
	v_pk_mul_f32 v[2:3], v[2:3], v[198:199]
	v_pk_mul_f32 v[12:13], v[12:13], v[184:185]
	v_pk_mul_f32 v[8:9], v[8:9], v[188:189]
	v_pk_mul_f32 v[4:5], v[4:5], v[192:193]
	v_pk_mul_f32 v[0:1], v[0:1], v[196:197]
	v_pk_mul_f32 v[30:31], v[30:31], v[186:187]
	v_pk_mul_f32 v[26:27], v[26:27], v[190:191]
	v_pk_mul_f32 v[22:23], v[22:23], v[194:195]
	v_pk_mul_f32 v[18:19], v[18:19], v[198:199]
	v_pk_mul_f32 v[28:29], v[28:29], v[184:185]
	v_pk_mul_f32 v[24:25], v[24:25], v[188:189]
	v_pk_mul_f32 v[20:21], v[20:21], v[192:193]
	v_pk_mul_f32 v[16:17], v[16:17], v[196:197]

; template <int DQK> __device__ __forceinline__ void partialSM(f32x16& p0, f32x16& p1, float& m_reg, float& mn, float& alpha) {
;     ...
;   if (__builtin_expect(__all(pmax - m_reg <= THR / SCALE), 1)) { mn = m_reg; alpha = 1.f; }
;   else { mn = fmaxf(m_reg, pmax); alpha = __builtin_amdgcn_exp2f((m_reg - mn) * C); m_reg = mn; }
;   float mnC = -mn * C;
; #pragma unroll
;   for (int r = 0; r < 16; ++r) p0[r] = fmaf(p0[r], C, mnC);
; #pragma unroll
;   for (int r = 0; r < 16; ++r) p1[r] = fmaf(p1[r], C, mnC);
; __device__ __forceinline__ void finishSM(f32x16& p0, f32x16& p1, float alpha, float& l_reg, bf16x8& pa0, bf16x8& pa1, bf16x8& pa2, bf16x8& pa3) {
; #pragma unroll
;   for (int r = 0; r < 16; ++r) p1[r] = __builtin_amdgcn_exp2f(p1[r]);
;   float ps = 0;
; #pragma unroll
;   for (int r = 0; r < 16; ++r) ps += p0[r];
; #pragma unroll
;   for (int r = 0; r < 16; ++r) ps += p1[r];
;   { auto rr = __builtin_amdgcn_permlane32_swap(__float_as_uint(ps), __float_as_uint(ps), false, false);
;     ps = __uint_as_float(rr[0]) + __uint_as_float(rr[1]); }
;   l_reg = l_reg * alpha + ps;
;     ...
;   PK4(p0, 0, pa0); PK4(p0, 8, pa1); PK4(p1, 0, pa2); PK4(p1, 8, pa3);
.Lmy_rare_a1:
	v_mov_b32_e32 v113, v112
	s_nop 1
	v_permlane32_swap_b32_e32 v112, v113
	v_max_f32_e32 v112, v112, v113
	v_max_f32_e32 v113, 0, v112
	v_sub_f32_e32 v32, v32, v113
	v_sub_f32_e32 v33, v33, v113
	v_sub_f32_e32 v34, v34, v113
	v_sub_f32_e32 v35, v35, v113
	v_sub_f32_e32 v36, v36, v113
	v_sub_f32_e32 v37, v37, v113
	v_sub_f32_e32 v38, v38, v113
	v_sub_f32_e32 v39, v39, v113
	v_sub_f32_e32 v40, v40, v113
	v_sub_f32_e32 v41, v41, v113
	v_sub_f32_e32 v42, v42, v113
	v_sub_f32_e32 v43, v43, v113
	v_sub_f32_e32 v44, v44, v113
	v_sub_f32_e32 v45, v45, v113
	v_sub_f32_e32 v46, v46, v113
	v_sub_f32_e32 v47, v47, v113
	v_sub_f32_e32 v48, v48, v113
	v_sub_f32_e32 v49, v49, v113
	v_sub_f32_e32 v50, v50, v113
	v_sub_f32_e32 v51, v51, v113
	v_sub_f32_e32 v52, v52, v113
	v_sub_f32_e32 v53, v53, v113
	v_sub_f32_e32 v54, v54, v113
	v_sub_f32_e32 v55, v55, v113
	v_sub_f32_e32 v56, v56, v113
	v_sub_f32_e32 v57, v57, v113
	v_sub_f32_e32 v58, v58, v113
	v_sub_f32_e32 v59, v59, v113
	v_sub_f32_e32 v60, v60, v113
	v_sub_f32_e32 v61, v61, v113
	v_sub_f32_e32 v62, v62, v113
	v_sub_f32_e32 v63, v63, v113
	v_sub_f32_e32 v210, v210, v113
	v_sub_f32_e32 v211, v211, v113
	v_sub_f32_e32 v212, v212, v113
	v_sub_f32_e32 v213, v213, v113
	v_sub_f32_e32 v214, v214, v113
	v_sub_f32_e32 v215, v215, v113
	v_sub_f32_e32 v216, v216, v113
	v_sub_f32_e32 v217, v217, v113
	v_sub_f32_e32 v218, v218, v113
	v_sub_f32_e32 v219, v219, v113
	v_sub_f32_e32 v220, v220, v113
	v_sub_f32_e32 v221, v221, v113
	v_sub_f32_e32 v222, v222, v113
	v_sub_f32_e32 v223, v223, v113
	v_sub_f32_e32 v224, v224, v113
	v_sub_f32_e32 v225, v225, v113
	v_sub_f32_e32 v113, 0, v113
	v_exp_f32_e32 v157, v113
	s_nop 0
	v_cmp_gt_f32_e32 vcc, 1.0, v157
	s_branch .Lmy_join_a1
.Lmy_rare_a2:
	v_mov_b32_e32 v113, v112
	s_nop 1
	v_permlane32_swap_b32_e32 v112, v113
	v_max_f32_e32 v112, v112, v113
	v_max_f32_e32 v113, 0, v112
	v_sub_f32_e32 v32, v32, v113
	v_sub_f32_e32 v33, v33, v113
	v_sub_f32_e32 v34, v34, v113
	v_sub_f32_e32 v35, v35, v113
	v_sub_f32_e32 v36, v36, v113
	v_sub_f32_e32 v37, v37, v113
	v_sub_f32_e32 v38, v38, v113
	v_sub_f32_e32 v39, v39, v113
	v_sub_f32_e32 v40, v40, v113
	v_sub_f32_e32 v41, v41, v113
	v_sub_f32_e32 v42, v42, v113
	v_sub_f32_e32 v43, v43, v113
	v_sub_f32_e32 v44, v44, v113
	v_sub_f32_e32 v45, v45, v113
	v_sub_f32_e32 v46, v46, v113
	v_sub_f32_e32 v47, v47, v113
	v_sub_f32_e32 v48, v48, v113
	v_sub_f32_e32 v49, v49, v113
	v_sub_f32_e32 v50, v50, v113
	v_sub_f32_e32 v51, v51, v113
	v_sub_f32_e32 v52, v52, v113
	v_sub_f32_e32 v53, v53, v113
	v_sub_f32_e32 v54, v54, v113
	v_sub_f32_e32 v55, v55, v113
	v_sub_f32_e32 v56, v56, v113
	v_sub_f32_e32 v57, v57, v113
	v_sub_f32_e32 v58, v58, v113
	v_sub_f32_e32 v59, v59, v113
	v_sub_f32_e32 v60, v60, v113
	v_sub_f32_e32 v61, v61, v113
	v_sub_f32_e32 v62, v62, v113
	v_sub_f32_e32 v63, v63, v113
	v_sub_f32_e32 v210, v210, v113
	v_sub_f32_e32 v211, v211, v113
	v_sub_f32_e32 v212, v212, v113
	v_sub_f32_e32 v213, v213, v113
	v_sub_f32_e32 v214, v214, v113
	v_sub_f32_e32 v215, v215, v113
	v_sub_f32_e32 v216, v216, v113
	v_sub_f32_e32 v217, v217, v113
	v_sub_f32_e32 v218, v218, v113
	v_sub_f32_e32 v219, v219, v113
	v_sub_f32_e32 v220, v220, v113
	v_sub_f32_e32 v221, v221, v113
	v_sub_f32_e32 v222, v222, v113
	v_sub_f32_e32 v223, v223, v113
	v_sub_f32_e32 v224, v224, v113
	v_sub_f32_e32 v225, v225, v113
	v_sub_f32_e32 v113, 0, v113
	v_exp_f32_e32 v117, v113
	s_nop 0
	v_cmp_gt_f32_e32 vcc, 1.0, v117
	s_branch .Lmy_join_a2
	.p2align 8
.Lmy_h1B:
	s_waitcnt vmcnt(0)
	ds_write_b128 v146, v[88:91] offset:32768
	ds_write_b128 v145, v[92:95] offset:16384
	v_mov_b32_e32 v117, v114
	v_mov_b32_e32 v157, v115
	v_mov_b32_e32 v164, v112
	v_add_f32_e32 v112, 0, v126
	v_add_f32_e32 v112, v160, v112
	v_add_f32_e32 v112, v127, v112
	v_add_f32_e32 v112, v161, v112
	v_add_f32_e32 v112, v158, v112
	v_add_f32_e32 v112, v162, v112
	v_add_f32_e32 v112, v159, v112
	v_add_f32_e32 v112, v163, v112
	v_add_f32_e32 v112, v118, v112
	v_add_f32_e32 v112, v121, v112
	v_add_f32_e32 v112, v119, v112
	v_add_f32_e32 v112, v122, v112
	v_add_f32_e32 v112, v120, v112
	v_add_f32_e32 v112, v123, v112
	v_add_f32_e32 v112, v124, v112
	v_mov_b32_e32 v165, v113
	v_add_f32_e32 v112, v125, v112
	v_add_f32_e32 v112, v117, v112
	v_add_f32_e32 v112, v157, v112
	v_add_f32_e32 v112, v164, v112
	v_add_f32_e32 v112, v165, v112
	v_add_f32_e32 v112, v108, v112
	v_add_f32_e32 v112, v109, v112
	v_add_f32_e32 v112, v104, v112
	v_add_f32_e32 v112, v105, v112
	v_add_f32_e32 v112, v102, v112
	v_add_f32_e32 v112, v103, v112
	v_add_f32_e32 v112, v110, v112
	v_add_f32_e32 v112, v111, v112
	v_add_f32_e32 v112, v106, v112
	v_add_f32_e32 v112, v107, v112
	v_add_f32_e32 v112, v100, v112
	v_add_f32_e32 v155, v101, v112
	v_cvt_pk_bf16_f32 v200, v126, v160
	v_cvt_pk_bf16_f32 v201, v127, v161
	v_cvt_pk_bf16_f32 v202, v158, v162
	v_cvt_pk_bf16_f32 v203, v159, v163
	v_cvt_pk_bf16_f32 v226, v118, v121
	v_cvt_pk_bf16_f32 v227, v119, v122
	v_cvt_pk_bf16_f32 v228, v120, v123
	v_cvt_pk_bf16_f32 v229, v124, v125
	v_cvt_pk_bf16_f32 v230, v117, v157
	v_cvt_pk_bf16_f32 v231, v164, v165
	v_cvt_pk_bf16_f32 v232, v108, v109
	v_cvt_pk_bf16_f32 v233, v104, v105
	v_cvt_pk_bf16_f32 v136, v102, v103
	v_cvt_pk_bf16_f32 v137, v110, v111
	v_cvt_pk_bf16_f32 v138, v106, v107
	v_cvt_pk_bf16_f32 v139, v100, v101
	s_lshl_b32 s0, s11, 6
	s_cmpk_lt_u32 s25, 0x7e
	s_cselect_b32 s1, s10, s24
	s_add_i32 s1, s1, s0
	s_addk_i32 s1, 0xffc0
	s_mul_i32 s1, s1, 0x300
	s_add_u32 s12, s18, s1
	s_addc_u32 s13, s19, 0
	s_cmpk_lt_u32 s25, 0x7f
	s_cselect_b32 s98, s10, s24
	s_add_i32 s98, s98, s0
	s_addk_i32 s98, 0xff80
	s_lshl_b32 s98, s98, 9
	s_add_u32 s98, s20, s98
	s_addc_u32 s99, s21, 0
	global_load_dwordx4 v[100:103], v134, s[12:13]
	global_load_dwordx4 v[108:111], v135, s[98:99]
	ds_read_b64_tr_b16 v[184:185], v144 offset:0
	ds_read_b64_tr_b16 v[186:187], v144 offset:0x800
	ds_read_b64_tr_b16 v[188:189], v144 offset:0x1000
	ds_read_b64_tr_b16 v[190:191], v144 offset:0x1800
	ds_read_b64_tr_b16 v[192:193], v144 offset:0x2000
	ds_read_b64_tr_b16 v[194:195], v144 offset:0x2800
	ds_read_b64_tr_b16 v[196:197], v144 offset:0x3000
	ds_read_b64_tr_b16 v[198:199], v144 offset:0x3800
	s_waitcnt lgkmcnt(0)
; template <int DQK> __device__ __forceinline__ void partialSM(f32x16& p0, f32x16& p1, float& m_reg, float& mn, float& alpha) {
;   constexpr float SCALE = (DQK == 96) ? 0.10206207261596577f : 0.125f;
;   constexpr float C = SCALE * 1.4426950408889634f;
;   float pmax = p0[0];
; #pragma unroll
;   for (int r = 1; r < 16; ++r) pmax = fmaxf(pmax, p0[r]);
; #pragma unroll
;   for (int r = 0; r < 16; ++r) pmax = fmaxf(pmax, p1[r]);
;   { auto rr = __builtin_amdgcn_permlane32_swap(__float_as_uint(pmax), __float_as_uint(pmax), false, false);
;     pmax = fmaxf(__uint_as_float(rr[0]), __uint_as_float(rr[1])); }
;   if (__builtin_expect(__all(pmax - m_reg <= THR / SCALE), 1)) { mn = m_reg; alpha = 1.f; }
;   else { mn = fmaxf(m_reg, pmax); alpha = __builtin_amdgcn_exp2f((m_reg - mn) * C); m_reg = mn; }
;   float mnC = -mn * C;
; #pragma unroll
;   for (int r = 0; r < 16; ++r) p0[r] = fmaf(p0[r], C, mnC);
; #pragma unroll
;   for (int r = 0; r < 16; ++r) p1[r] = fmaf(p1[r], C, mnC);
; #pragma unroll
;   for (int r = 0; r < 16; ++r) p0[r] = __builtin_amdgcn_exp2f(p0[r]);
; }
; __device__ __forceinline__ void finishSM(f32x16& p0, f32x16& p1, float alpha, float& l_reg, bf16x8& pa0, bf16x8& pa1, bf16x8& pa2, bf16x8& pa3) {
; #pragma unroll
;   for (int r = 0; r < 16; ++r) p1[r] = __builtin_amdgcn_exp2f(p1[r]);
; template <int D0> __device__ __forceinline__ void pv_one(f32x16& od, int vb, bf16x8 pa0, bf16x8 pa1, bf16x8 pa2, bf16x8 pa3) {
;   const s16x4 l0 = tr_read<v_rd_off(D0, 0, 0)>(vb), h0 = tr_read<v_rd_off(D0, 0, 1)>(vb), l1 = tr_read<v_rd_off(D0, 1, 0)>(vb), h1 = tr_read<v_rd_off(D0, 1, 1)>(vb);
;   const s16x4 l2 = tr_read<v_rd_off(D0, 2, 0)>(vb), h2 = tr_read<v_rd_off(D0, 2, 1)>(vb), l3 = tr_read<v_rd_off(D0, 3, 0)>(vb), h3 = tr_read<v_rd_off(D0, 3, 1)>(vb);
;   asm volatile("s_waitcnt lgkmcnt(0)" ::: "memory"); SBAR();
;   od = __builtin_amdgcn_mfma_f32_32x32x16_bf16(pa0, PKLH(l0, h0), od, 0, 0, 0);
;   od = __builtin_amdgcn_mfma_f32_32x32x16_bf16(pa1, PKLH(l1, h1), od, 0, 0, 0);
;   od = __builtin_amdgcn_mfma_f32_32x32x16_bf16(pa2, PKLH(l2, h2), od, 0, 0, 0);
;   od = __builtin_amdgcn_mfma_f32_32x32x16_bf16(pa3, PKLH(l3, h3), od, 0, 0, 0);
; }
; __device__ __forceinline__ void pv_d0(f32x16* o, int vb, bf16x8 pa0, bf16x8 pa1, bf16x8 pa2, bf16x8 pa3) {
;   pv_one<0>(o[0], vb, pa0, pa1, pa2, pa3); pv_one<1>(o[1], vb, pa0, pa1, pa2, pa3);
; }
	s_nop 0
	v_mfma_f32_32x32x16_bf16 v[0:15], v[200:203], v[184:187], v[0:15]
	ds_read_b64_tr_b16 v[184:185], v144 offset:0x200
	ds_read_b64_tr_b16 v[186:187], v144 offset:0xa00
	v_mfma_f32_32x32x16_bf16 v[0:15], v[226:229], v[188:191], v[0:15]
	ds_read_b64_tr_b16 v[188:189], v144 offset:0x1200
	ds_read_b64_tr_b16 v[190:191], v144 offset:0x1a00
	v_mfma_f32_32x32x16_bf16 v[0:15], v[230:233], v[192:195], v[0:15]
	ds_read_b64_tr_b16 v[192:193], v144 offset:0x2200
	ds_read_b64_tr_b16 v[194:195], v144 offset:0x2a00
	v_mfma_f32_32x32x16_bf16 v[0:15], v[136:139], v[196:199], v[0:15]
	ds_read_b64_tr_b16 v[196:197], v144 offset:0x3200
	ds_read_b64_tr_b16 v[198:199], v144 offset:0x3a00
	s_waitcnt lgkmcnt(0)
	v_mfma_f32_32x32x16_bf16 v[16:31], v[200:203], v[184:187], v[16:31]
	v_mfma_f32_32x32x16_bf16 v[16:31], v[226:229], v[188:191], v[16:31]
	v_mfma_f32_32x32x16_bf16 v[16:31], v[230:233], v[192:195], v[16:31]
	v_mfma_f32_32x32x16_bf16 v[16:31], v[136:139], v[196:199], v[16:31]
	ds_read_b128 v[32:35], v148 offset:49152
	ds_read_b128 v[36:39], v148 offset:57344
	ds_read_b128 v[164:167], v152 offset:49152
	ds_read_b128 v[168:171], v152 offset:57344
	s_waitcnt lgkmcnt(3)
	v_mfma_f32_32x32x16_bf16 v[48:63], v[32:35], v[84:87], v[210:225]
	s_waitcnt lgkmcnt(2)
	v_mfma_f32_32x32x16_bf16 v[32:47], v[36:39], v[84:87], v[210:225]
	s_waitcnt lgkmcnt(1)
	v_mfma_f32_32x32x16_bf16 v[48:63], v[164:167], v[80:83], v[48:63]
	s_waitcnt lgkmcnt(0)
	v_mfma_f32_32x32x16_bf16 v[32:47], v[168:171], v[80:83], v[32:47]
	ds_read_b128 v[164:167], v151 offset:49152
	ds_read_b128 v[168:171], v151 offset:57344
	s_waitcnt lgkmcnt(1)
	v_mfma_f32_32x32x16_bf16 v[48:63], v[164:167], v[76:79], v[48:63]
	s_waitcnt lgkmcnt(0)
	v_mfma_f32_32x32x16_bf16 v[32:47], v[168:171], v[76:79], v[32:47]
	ds_read_b128 v[164:167], v149 offset:49152
	ds_read_b128 v[168:171], v149 offset:57344
	s_waitcnt lgkmcnt(1)
	v_mfma_f32_32x32x16_bf16 v[48:63], v[164:167], v[72:75], v[48:63]
	s_waitcnt lgkmcnt(0)
	v_mfma_f32_32x32x16_bf16 v[32:47], v[168:171], v[72:75], v[32:47]
	ds_read_b128 v[164:167], v150 offset:49152
	ds_read_b128 v[168:171], v150 offset:57344
	s_waitcnt lgkmcnt(1)
	v_mfma_f32_32x32x16_bf16 v[48:63], v[164:167], v[68:71], v[48:63]
	s_waitcnt lgkmcnt(0)
	v_mfma_f32_32x32x16_bf16 v[32:47], v[168:171], v[68:71], v[32:47]
	ds_read_b128 v[164:167], v153 offset:49152
	ds_read_b128 v[168:171], v153 offset:57344
	s_waitcnt lgkmcnt(1)
	v_mfma_f32_32x32x16_bf16 v[48:63], v[164:167], v[64:67], v[48:63]
	s_waitcnt lgkmcnt(0)
	v_mfma_f32_32x32x16_bf16 v[32:47], v[168:171], v[64:67], v[32:47]
	s_nop 7
	s_nop 4
	v_max_f32_e32 v112, v48, v49
	v_max3_f32 v112, v112, v50, v51
	v_max3_f32 v112, v112, v52, v53
	v_max3_f32 v112, v112, v54, v55
	v_max3_f32 v112, v112, v56, v57
	v_max3_f32 v112, v112, v58, v59
	v_max3_f32 v112, v112, v60, v61
	v_max3_f32 v112, v112, v62, v63
	v_max3_f32 v112, v112, v32, v33
	v_max3_f32 v112, v112, v34, v35
	v_max3_f32 v112, v112, v36, v37
	v_max3_f32 v112, v112, v38, v39
	v_max3_f32 v112, v112, v40, v41
	v_max3_f32 v112, v112, v42, v43
	v_max3_f32 v112, v112, v44, v45
	v_max3_f32 v112, v112, v46, v47
	v_cmp_ge_f32_e32 vcc, s80, v112
	s_cmp_eq_u64 vcc, exec
	s_cbranch_scc0 .Lmy_rare_b1
	v_mov_b32_e32 v157, 1.0
	s_mov_b64 vcc, 0
.Lmy_join_b1:
	v_exp_f32_e32 v112, v48
	v_exp_f32_e32 v127, v49
	v_exp_f32_e32 v113, v50
	v_exp_f32_e32 v126, v51
	v_exp_f32_e32 v114, v52
	v_exp_f32_e32 v125, v53
	v_exp_f32_e32 v115, v54
	v_exp_f32_e32 v124, v55
	v_exp_f32_e32 v116, v56
	v_exp_f32_e32 v123, v57
	v_exp_f32_e32 v117, v58
	v_exp_f32_e32 v122, v59
	v_exp_f32_e32 v118, v60
	v_exp_f32_e32 v121, v61
	v_exp_f32_e32 v119, v62
	v_exp_f32_e32 v120, v63
	v_exp_f32_e32 v164, v42
	v_exp_f32_e32 v165, v43
	v_exp_f32_e32 v167, v32
	v_exp_f32_e32 v168, v33
	v_exp_f32_e32 v169, v34
	v_exp_f32_e32 v170, v35
	v_exp_f32_e32 v171, v36
	v_exp_f32_e32 v172, v37
	v_exp_f32_e32 v160, v38
	v_exp_f32_e32 v161, v39
	v_exp_f32_e32 v162, v40
	v_exp_f32_e32 v163, v41
	v_exp_f32_e32 v166, v44
	v_exp_f32_e32 v173, v45
	v_exp_f32_e32 v174, v46
	v_exp_f32_e32 v159, v47
	s_cbranch_vccz .Lmy_h1B_304
	s_and_saveexec_b64 s[12:13], s[4:5]
	ds_write_b32 v141, v157 offset:128
	s_or_b64 exec, exec, s[12:13]
	s_waitcnt lgkmcnt(0)
	ds_read_b128 v[184:187], v129 offset:224
	ds_read_b128 v[188:191], v129 offset:192
	ds_read_b128 v[192:195], v129 offset:160
	ds_read_b128 v[196:199], v129 offset:128
	s_waitcnt lgkmcnt(3)
	v_pk_mul_f32 v[14:15], v[14:15], v[186:187]
	s_waitcnt lgkmcnt(2)
	v_pk_mul_f32 v[10:11], v[10:11], v[190:191]
	s_waitcnt lgkmcnt(1)
	v_pk_mul_f32 v[6:7], v[6:7], v[194:195]
	s_waitcnt lgkmcnt(0)
	v_pk_mul_f32 v[2:3], v[2:3], v[198:199]
	v_pk_mul_f32 v[12:13], v[12:13], v[184:185]
	v_pk_mul_f32 v[8:9], v[8:9], v[188:189]
	v_pk_mul_f32 v[4:5], v[4:5], v[192:193]
	v_pk_mul_f32 v[0:1], v[0:1], v[196:197]
	v_pk_mul_f32 v[30:31], v[30:31], v[186:187]
	v_pk_mul_f32 v[26:27], v[26:27], v[190:191]
	v_pk_mul_f32 v[22:23], v[22:23], v[194:195]
	v_pk_mul_f32 v[18:19], v[18:19], v[198:199]
	v_pk_mul_f32 v[28:29], v[28:29], v[184:185]
	v_pk_mul_f32 v[24:25], v[24:25], v[188:189]
	v_pk_mul_f32 v[20:21], v[20:21], v[192:193]
	v_pk_mul_f32 v[16:17], v[16:17], v[196:197]
; #define SBAR() __builtin_amdgcn_sched_barrier(0)
; #define SLOAD(i, j) do { const long kr_ = KROW(j); sr_[i].vs0 = ld8(Vp + (kr_ + sr) * ldv + sc); sr_[i].ks0 = ld8(Kp + (kr_ + sr) * ldk + sc); \
;     if (DQK == 96) sr_[i].ks1 = ld8(Kp + (kr_ + sr2) * ldk + sc2); } while (0)
; __device__ __forceinline__ void finishSM(f32x16& p0, f32x16& p1, float alpha, float& l_reg, bf16x8& pa0, bf16x8& pa1, bf16x8& pa2, bf16x8& pa3) {
; #pragma unroll
;   for (int r = 0; r < 16; ++r) p1[r] = __builtin_amdgcn_exp2f(p1[r]);
;   float ps = 0;
; #pragma unroll
;   for (int r = 0; r < 16; ++r) ps += p0[r];
; #pragma unroll
;   for (int r = 0; r < 16; ++r) ps += p1[r];
;   { auto rr = __builtin_amdgcn_permlane32_swap(__float_as_uint(ps), __float_as_uint(ps), false, false);
;     ps = __uint_as_float(rr[0]) + __uint_as_float(rr[1]); }
;   l_reg = l_reg * alpha + ps;
;     ...
;   PK4(p0, 0, pa0); PK4(p0, 8, pa1); PK4(p1, 0, pa2); PK4(p1, 8, pa3);
; template <int DQK, int MODE, int ldq, int ldk, int ldv> ...
;     ...
;     SBAR(); qkt<DQK>(pA0, pA1, K_lds, qr, r32, hi);
;     finishSM(pB0, pB1, alB, l_reg, pa0, pa1, pa2, pa3); SBAR();
;     if (j + 3 < NT) SLOAD(SE, j + 3); SBAR();
.Lmy_h1B_304:
	s_waitcnt lgkmcnt(0)
	s_barrier
	s_waitcnt vmcnt(0)
	ds_write_b128 v146, v[100:103] offset:49152
	ds_write_b128 v145, v[108:111]
	v_mov_b32_e32 v175, v164
	v_add_f32_e32 v164, 0, v112
	v_add_f32_e32 v164, v127, v164
	v_add_f32_e32 v164, v113, v164
	v_add_f32_e32 v164, v126, v164
	v_add_f32_e32 v164, v114, v164
	v_add_f32_e32 v164, v125, v164
	v_add_f32_e32 v164, v115, v164
	v_add_f32_e32 v164, v124, v164
	v_add_f32_e32 v164, v116, v164
	v_add_f32_e32 v164, v123, v164
	v_add_f32_e32 v164, v117, v164
	v_add_f32_e32 v164, v122, v164
	v_add_f32_e32 v164, v118, v164
	v_add_f32_e32 v164, v121, v164
	v_add_f32_e32 v164, v119, v164
	v_add_f32_e32 v164, v120, v164
	v_add_f32_e32 v164, v167, v164
	v_add_f32_e32 v164, v168, v164
	v_add_f32_e32 v164, v169, v164
	v_add_f32_e32 v164, v170, v164
	v_add_f32_e32 v164, v171, v164
	v_add_f32_e32 v164, v172, v164
	v_add_f32_e32 v164, v160, v164
	v_add_f32_e32 v164, v161, v164
	v_add_f32_e32 v164, v162, v164
	v_add_f32_e32 v164, v163, v164
	v_add_f32_e32 v164, v175, v164
	v_cvt_pk_bf16_f32 v200, v112, v127
	v_cvt_pk_bf16_f32 v201, v113, v126
	v_cvt_pk_bf16_f32 v202, v114, v125
	v_cvt_pk_bf16_f32 v203, v115, v124
	v_cvt_pk_bf16_f32 v226, v116, v123
	v_cvt_pk_bf16_f32 v227, v117, v122
	v_mov_b32_e32 v176, v165
	v_cvt_pk_bf16_f32 v228, v118, v121
	v_cvt_pk_bf16_f32 v229, v119, v120
	v_cvt_pk_bf16_f32 v230, v167, v168
	v_cvt_pk_bf16_f32 v231, v169, v170
	v_cvt_pk_bf16_f32 v232, v171, v172
	s_nop 0
	v_add_f32_e32 v164, v176, v164
	v_add_f32_e32 v164, v166, v164
	v_add_f32_e32 v164, v173, v164
	v_add_f32_e32 v164, v174, v164
	v_add_f32_e32 v164, v159, v164
	v_cvt_pk_bf16_f32 v233, v160, v161
	v_cvt_pk_bf16_f32 v136, v162, v163
	v_cvt_pk_bf16_f32 v137, v175, v176
	v_cvt_pk_bf16_f32 v138, v166, v173
	v_cvt_pk_bf16_f32 v139, v174, v159
	s_lshl_b32 s0, s11, 6
	s_cmpk_lt_u32 s25, 0x7e
	s_cselect_b32 s98, s10, s24
	s_add_i32 s98, s98, s0
	s_addk_i32 s98, 0xffc0
	s_lshl_b32 s98, s98, 9
	s_add_u32 s98, s20, s98
	s_addc_u32 s99, s21, 0
	global_load_dwordx4 v[92:95], v135, s[98:99]
	s_cmpk_gt_u32 s25, 0x80
	s_cbranch_scc1 .Lmy_h2B_306
	s_cmpk_lt_u32 s25, 0x7d
	s_cselect_b32 s1, s10, s24
	s_add_i32 s1, s1, s0
	s_mul_i32 s1, s1, 0x300
	s_add_u32 s12, s18, s1
	s_addc_u32 s13, s19, 0
	global_load_dwordx4 v[88:91], v134, s[12:13]
; template <int DQK> __device__ __forceinline__ void partialSM(f32x16& p0, f32x16& p1, float& m_reg, float& mn, float& alpha) {
;   constexpr float SCALE = (DQK == 96) ? 0.10206207261596577f : 0.125f;
;   constexpr float C = SCALE * 1.4426950408889634f;
;   float pmax = p0[0];
; #pragma unroll
;   for (int r = 1; r < 16; ++r) pmax = fmaxf(pmax, p0[r]);
; #pragma unroll
;   for (int r = 0; r < 16; ++r) pmax = fmaxf(pmax, p1[r]);
;   { auto rr = __builtin_amdgcn_permlane32_swap(__float_as_uint(pmax), __float_as_uint(pmax), false, false);
;     pmax = fmaxf(__uint_as_float(rr[0]), __uint_as_float(rr[1])); }
;   if (__builtin_expect(__all(pmax - m_reg <= THR / SCALE), 1)) { mn = m_reg; alpha = 1.f; }
;   else { mn = fmaxf(m_reg, pmax); alpha = __builtin_amdgcn_exp2f((m_reg - mn) * C); m_reg = mn; }
;   float mnC = -mn * C;
; #pragma unroll
;   for (int r = 0; r < 16; ++r) p0[r] = fmaf(p0[r], C, mnC);
; #pragma unroll
;   for (int r = 0; r < 16; ++r) p1[r] = fmaf(p1[r], C, mnC);
; #pragma unroll
;   for (int r = 0; r < 16; ++r) p0[r] = __builtin_amdgcn_exp2f(p0[r]);
; }
; __device__ __forceinline__ void finishSM(f32x16& p0, f32x16& p1, float alpha, float& l_reg, bf16x8& pa0, bf16x8& pa1, bf16x8& pa2, bf16x8& pa3) {
; #pragma unroll
;   for (int r = 0; r < 16; ++r) p1[r] = __builtin_amdgcn_exp2f(p1[r]);
;   float ps = 0;
; #pragma unroll
;   for (int r = 0; r < 16; ++r) ps += p0[r];
; #pragma unroll
;   for (int r = 0; r < 16; ++r) ps += p1[r];
;   { auto rr = __builtin_amdgcn_permlane32_swap(__float_as_uint(ps), __float_as_uint(ps), false, false);
;     ps = __uint_as_float(rr[0]) + __uint_as_float(rr[1]); }
;   l_reg = l_reg * alpha + ps;
; template <int D0> __device__ __forceinline__ void pv_one(f32x16& od, int vb, bf16x8 pa0, bf16x8 pa1, bf16x8 pa2, bf16x8 pa3) {
;   const s16x4 l0 = tr_read<v_rd_off(D0, 0, 0)>(vb), h0 = tr_read<v_rd_off(D0, 0, 1)>(vb), l1 = tr_read<v_rd_off(D0, 1, 0)>(vb), h1 = tr_read<v_rd_off(D0, 1, 1)>(vb);
;   const s16x4 l2 = tr_read<v_rd_off(D0, 2, 0)>(vb), h2 = tr_read<v_rd_off(D0, 2, 1)>(vb), l3 = tr_read<v_rd_off(D0, 3, 0)>(vb), h3 = tr_read<v_rd_off(D0, 3, 1)>(vb);
;   asm volatile("s_waitcnt lgkmcnt(0)" ::: "memory"); SBAR();
;   od = __builtin_amdgcn_mfma_f32_32x32x16_bf16(pa0, PKLH(l0, h0), od, 0, 0, 0);
;   od = __builtin_amdgcn_mfma_f32_32x32x16_bf16(pa1, PKLH(l1, h1), od, 0, 0, 0);
.Lmy_h2B_306:
	ds_read_b64_tr_b16 v[184:185], v143 offset:0
	ds_read_b64_tr_b16 v[186:187], v143 offset:0x800
	ds_read_b64_tr_b16 v[188:189], v143 offset:0x1000
	ds_read_b64_tr_b16 v[190:191], v143 offset:0x1800
	ds_read_b64_tr_b16 v[192:193], v143 offset:0x2000
	ds_read_b64_tr_b16 v[194:195], v143 offset:0x2800
	ds_read_b64_tr_b16 v[196:197], v143 offset:0x3000
	ds_read_b64_tr_b16 v[198:199], v143 offset:0x3800
	s_waitcnt lgkmcnt(0)
	s_nop 0
	v_mfma_f32_32x32x16_bf16 v[0:15], v[200:203], v[184:187], v[0:15]
	ds_read_b64_tr_b16 v[184:185], v143 offset:0x200
	ds_read_b64_tr_b16 v[186:187], v143 offset:0xa00
	v_mfma_f32_32x32x16_bf16 v[0:15], v[226:229], v[188:191], v[0:15]
	ds_read_b64_tr_b16 v[188:189], v143 offset:0x1200
	ds_read_b64_tr_b16 v[190:191], v143 offset:0x1a00
	v_mfma_f32_32x32x16_bf16 v[0:15], v[230:233], v[192:195], v[0:15]
	ds_read_b64_tr_b16 v[192:193], v143 offset:0x2200
	ds_read_b64_tr_b16 v[194:195], v143 offset:0x2a00
	v_mfma_f32_32x32x16_bf16 v[0:15], v[136:139], v[196:199], v[0:15]
	ds_read_b64_tr_b16 v[196:197], v143 offset:0x3200
	ds_read_b64_tr_b16 v[198:199], v143 offset:0x3a00
	s_waitcnt lgkmcnt(0)
	v_mfma_f32_32x32x16_bf16 v[16:31], v[200:203], v[184:187], v[16:31]
	v_mfma_f32_32x32x16_bf16 v[16:31], v[226:229], v[188:191], v[16:31]
	v_mfma_f32_32x32x16_bf16 v[16:31], v[230:233], v[192:195], v[16:31]
	v_mfma_f32_32x32x16_bf16 v[16:31], v[136:139], v[196:199], v[16:31]
	ds_read_b128 v[32:35], v148 offset:32768
	ds_read_b128 v[36:39], v148 offset:40960
	ds_read_b128 v[176:179], v152 offset:32768
	ds_read_b128 v[180:183], v152 offset:40960
	s_waitcnt lgkmcnt(3)
	v_mfma_f32_32x32x16_bf16 v[48:63], v[32:35], v[84:87], v[210:225]
	s_waitcnt lgkmcnt(2)
	v_mfma_f32_32x32x16_bf16 v[32:47], v[36:39], v[84:87], v[210:225]
	s_waitcnt lgkmcnt(1)
	v_mfma_f32_32x32x16_bf16 v[48:63], v[176:179], v[80:83], v[48:63]
	s_waitcnt lgkmcnt(0)
	v_mfma_f32_32x32x16_bf16 v[32:47], v[180:183], v[80:83], v[32:47]
	ds_read_b128 v[176:179], v151 offset:32768
	ds_read_b128 v[180:183], v151 offset:40960
	s_waitcnt lgkmcnt(1)
	v_mfma_f32_32x32x16_bf16 v[48:63], v[176:179], v[76:79], v[48:63]
	s_waitcnt lgkmcnt(0)
	v_mfma_f32_32x32x16_bf16 v[32:47], v[180:183], v[76:79], v[32:47]
	ds_read_b128 v[176:179], v149 offset:32768
	ds_read_b128 v[180:183], v149 offset:40960
	s_waitcnt lgkmcnt(1)
	v_mfma_f32_32x32x16_bf16 v[48:63], v[176:179], v[72:75], v[48:63]
	s_waitcnt lgkmcnt(0)
	v_mfma_f32_32x32x16_bf16 v[32:47], v[180:183], v[72:75], v[32:47]
	ds_read_b128 v[176:179], v150 offset:32768
	ds_read_b128 v[180:183], v150 offset:40960
	s_waitcnt lgkmcnt(1)
	v_mfma_f32_32x32x16_bf16 v[48:63], v[176:179], v[68:71], v[48:63]
	s_waitcnt lgkmcnt(0)
	v_mfma_f32_32x32x16_bf16 v[32:47], v[180:183], v[68:71], v[32:47]
	ds_read_b128 v[176:179], v153 offset:32768
	ds_read_b128 v[180:183], v153 offset:40960
	s_waitcnt lgkmcnt(1)
	v_mfma_f32_32x32x16_bf16 v[48:63], v[176:179], v[64:67], v[48:63]
	s_waitcnt lgkmcnt(0)
	v_mfma_f32_32x32x16_bf16 v[32:47], v[180:183], v[64:67], v[32:47]
	s_nop 7
	s_nop 4
	v_max_f32_e32 v112, v48, v49
	v_max3_f32 v112, v112, v50, v51
	v_max3_f32 v112, v112, v52, v53
	v_max3_f32 v112, v112, v54, v55
	v_max3_f32 v112, v112, v56, v57
	v_max3_f32 v112, v112, v58, v59
	v_max3_f32 v112, v112, v60, v61
	v_max3_f32 v112, v112, v62, v63
	v_max3_f32 v112, v112, v32, v33
	v_max3_f32 v112, v112, v34, v35
	v_max3_f32 v112, v112, v36, v37
	v_max3_f32 v112, v112, v38, v39
	v_max3_f32 v112, v112, v40, v41
	v_max3_f32 v112, v112, v42, v43
	v_max3_f32 v112, v112, v44, v45
	v_max3_f32 v112, v112, v46, v47
	v_cmp_ge_f32_e32 vcc, s80, v112
	s_cmp_eq_u64 vcc, exec
	s_cbranch_scc0 .Lmy_rare_b2
	v_mov_b32_e32 v117, 1.0
	s_mov_b64 vcc, 0
.Lmy_join_b2:
	v_exp_f32_e32 v126, v48
	v_exp_f32_e32 v160, v49
	v_exp_f32_e32 v127, v50
	v_exp_f32_e32 v161, v51
	v_exp_f32_e32 v158, v52
	v_exp_f32_e32 v162, v53
	v_exp_f32_e32 v159, v54
	v_exp_f32_e32 v163, v55
	v_exp_f32_e32 v118, v56
	v_exp_f32_e32 v121, v57
	v_exp_f32_e32 v119, v58
	v_exp_f32_e32 v122, v59
	v_exp_f32_e32 v120, v60
	v_exp_f32_e32 v123, v61
	v_exp_f32_e32 v124, v62
	v_exp_f32_e32 v125, v63
	v_exp_f32_e32 v114, v32
	v_exp_f32_e32 v115, v33
	v_exp_f32_e32 v112, v34
	v_exp_f32_e32 v113, v35
	v_exp_f32_e32 v108, v36
	v_exp_f32_e32 v109, v37
	v_exp_f32_e32 v104, v38
	v_exp_f32_e32 v105, v39
	v_exp_f32_e32 v102, v40
	v_exp_f32_e32 v103, v41
	v_exp_f32_e32 v110, v42
	v_exp_f32_e32 v111, v43
	v_exp_f32_e32 v106, v44
	v_exp_f32_e32 v107, v45
	v_exp_f32_e32 v101, v47
	v_exp_f32_e32 v100, v46
	v_fmac_f32_e32 v155, v154, v142
	v_fma_f32 v142, v155, v157, v164
	s_cbranch_vccz .Lmy_h2B_310
	s_and_saveexec_b64 s[12:13], s[4:5]
	ds_write_b32 v141, v117 offset:128
	s_or_b64 exec, exec, s[12:13]
	s_waitcnt lgkmcnt(0)
	ds_read_b128 v[184:187], v129 offset:224
	ds_read_b128 v[188:191], v129 offset:192
	ds_read_b128 v[192:195], v129 offset:160
	ds_read_b128 v[196:199], v129 offset:128
	s_waitcnt lgkmcnt(3)
	v_pk_mul_f32 v[14:15], v[14:15], v[186:187]
	s_waitcnt lgkmcnt(2)
	v_pk_mul_f32 v[10:11], v[10:11], v[190:191]
	s_waitcnt lgkmcnt(1)
	v_pk_mul_f32 v[6:7], v[6:7], v[194:195]
	s_waitcnt lgkmcnt(0)
	v_pk_mul_f32 v[2:3], v[2:3], v[198:199]
	v_pk_mul_f32 v[12:13], v[12:13], v[184:185]
	v_pk_mul_f32 v[8:9], v[8:9], v[188:189]
	v_pk_mul_f32 v[4:5], v[4:5], v[192:193]
	v_pk_mul_f32 v[0:1], v[0:1], v[196:197]
	v_pk_mul_f32 v[30:31], v[30:31], v[186:187]
	v_pk_mul_f32 v[26:27], v[26:27], v[190:191]
	v_pk_mul_f32 v[22:23], v[22:23], v[194:195]
	v_pk_mul_f32 v[18:19], v[18:19], v[198:199]
	v_pk_mul_f32 v[28:29], v[28:29], v[184:185]
	v_pk_mul_f32 v[24:25], v[24:25], v[188:189]
	v_pk_mul_f32 v[20:21], v[20:21], v[192:193]
	v_pk_mul_f32 v[16:17], v[16:17], v[196:197]

; #define SBAR() __builtin_amdgcn_sched_barrier(0)
; #define BIAS(P0, P1, j) do { if (MODE == 1) { SBAR(); if ((j) >= nA) na_bias(P0, P1, na, rs0 + (j) - nA, hi); SBAR(); } } while (0)
; template <int DQK> __device__ __forceinline__ void partialSM(f32x16& p0, f32x16& p1, float& m_reg, float& mn, float& alpha) {
;     ...
;   if (__builtin_expect(__all(pmax - m_reg <= THR / SCALE), 1)) { mn = m_reg; alpha = 1.f; }
;   else { mn = fmaxf(m_reg, pmax); alpha = __builtin_amdgcn_exp2f((m_reg - mn) * C); m_reg = mn; }
;   float mnC = -mn * C;
; #pragma unroll
;   for (int r = 0; r < 16; ++r) p0[r] = fmaf(p0[r], C, mnC);
; #pragma unroll
;   for (int r = 0; r < 16; ++r) p1[r] = fmaf(p1[r], C, mnC);
; template <int DQK, int MODE, int ldq, int ldk, int ldv> ...
;     ...
;   SBAR(); qkt<DQK>(pB0, pB1, K_lds + SHM_K, qr, r32, hi);
;   finishSM(pA0, pA1, alA, l_reg, pa0, pa1, pa2, pa3); SBAR();
;   pv_d0(o, vb0, pa0, pa1, pa2, pa3); BIAS(pB0, pB1, NT - 1); partialSM<DQK>(pB0, pB1, m_reg, mnB, alB);
.Lmy_rare_b2:
	v_mov_b32_e32 v113, v112
	s_nop 1
	v_permlane32_swap_b32_e32 v112, v113
	v_max_f32_e32 v112, v112, v113
	v_max_f32_e32 v113, 0, v112
	v_sub_f32_e32 v32, v32, v113
	v_sub_f32_e32 v33, v33, v113
	v_sub_f32_e32 v34, v34, v113
	v_sub_f32_e32 v35, v35, v113
	v_sub_f32_e32 v36, v36, v113
	v_sub_f32_e32 v37, v37, v113
	v_sub_f32_e32 v38, v38, v113
	v_sub_f32_e32 v39, v39, v113
	v_sub_f32_e32 v40, v40, v113
	v_sub_f32_e32 v41, v41, v113
	v_sub_f32_e32 v42, v42, v113
	v_sub_f32_e32 v43, v43, v113
	v_sub_f32_e32 v44, v44, v113
	v_sub_f32_e32 v45, v45, v113
	v_sub_f32_e32 v46, v46, v113
	v_sub_f32_e32 v47, v47, v113
	v_sub_f32_e32 v48, v48, v113
	v_sub_f32_e32 v49, v49, v113
	v_sub_f32_e32 v50, v50, v113
	v_sub_f32_e32 v51, v51, v113
	v_sub_f32_e32 v52, v52, v113
	v_sub_f32_e32 v53, v53, v113
	v_sub_f32_e32 v54, v54, v113
	v_sub_f32_e32 v55, v55, v113
	v_sub_f32_e32 v56, v56, v113
	v_sub_f32_e32 v57, v57, v113
	v_sub_f32_e32 v58, v58, v113
	v_sub_f32_e32 v59, v59, v113
	v_sub_f32_e32 v60, v60, v113
	v_sub_f32_e32 v61, v61, v113
	v_sub_f32_e32 v62, v62, v113
	v_sub_f32_e32 v63, v63, v113
	v_sub_f32_e32 v210, v210, v113
	v_sub_f32_e32 v211, v211, v113
	v_sub_f32_e32 v212, v212, v113
	v_sub_f32_e32 v213, v213, v113
	v_sub_f32_e32 v214, v214, v113
	v_sub_f32_e32 v215, v215, v113
	v_sub_f32_e32 v216, v216, v113
	v_sub_f32_e32 v217, v217, v113
	v_sub_f32_e32 v218, v218, v113
	v_sub_f32_e32 v219, v219, v113
	v_sub_f32_e32 v220, v220, v113
	v_sub_f32_e32 v221, v221, v113
	v_sub_f32_e32 v222, v222, v113
	v_sub_f32_e32 v223, v223, v113
	v_sub_f32_e32 v224, v224, v113
	v_sub_f32_e32 v225, v225, v113
	v_sub_f32_e32 v113, 0, v113
	v_exp_f32_e32 v117, v113
	s_nop 0
	v_cmp_gt_f32_e32 vcc, 1.0, v117
	s_branch .Lmy_join_b2
.LBB0_312:
	v_sub_f32_e32 v116, 0, v210
	v_mov_b32_e32 v239, v142
	s_nop 1
	v_permlane32_swap_b32_e32 v142, v239
	v_add_f32_e32 v142, v142, v239
	s_waitcnt vmcnt(0)
	ds_write_b128 v145, v[92:95] offset:16384
	ds_read_b128 v[32:35], v148 offset:49152
	ds_read_b128 v[36:39], v148 offset:57344
	s_waitcnt lgkmcnt(1)
	v_mfma_f32_32x32x16_bf16 v[48:63], v[32:35], v[84:87], 0
	s_waitcnt lgkmcnt(0)
	v_mfma_f32_32x32x16_bf16 v[32:47], v[36:39], v[84:87], 0
	ds_read_b128 v[84:87], v152 offset:49152
	ds_read_b128 v[88:91], v152 offset:57344
	s_waitcnt lgkmcnt(1)
	v_mfma_f32_32x32x16_bf16 v[48:63], v[84:87], v[80:83], v[48:63]
	s_waitcnt lgkmcnt(0)
	v_mfma_f32_32x32x16_bf16 v[32:47], v[88:91], v[80:83], v[32:47]
	ds_read_b128 v[80:83], v151 offset:49152
	ds_read_b128 v[84:87], v151 offset:57344
	v_mov_b32_e32 v88, v100
	v_mov_b32_e32 v89, v101
	s_waitcnt lgkmcnt(1)
	v_mfma_f32_32x32x16_bf16 v[48:63], v[80:83], v[76:79], v[48:63]
	s_waitcnt lgkmcnt(0)
	v_mfma_f32_32x32x16_bf16 v[32:47], v[84:87], v[76:79], v[32:47]
	ds_read_b128 v[76:79], v149 offset:49152
	ds_read_b128 v[80:83], v149 offset:57344
	v_mov_b32_e32 v84, v110
	v_mov_b32_e32 v85, v111
	v_mov_b32_e32 v86, v106
	v_mov_b32_e32 v87, v107
	s_waitcnt lgkmcnt(1)
	v_mfma_f32_32x32x16_bf16 v[48:63], v[76:79], v[72:75], v[48:63]
	s_waitcnt lgkmcnt(0)
	v_mfma_f32_32x32x16_bf16 v[32:47], v[80:83], v[72:75], v[32:47]
	ds_read_b128 v[72:75], v150 offset:49152
	ds_read_b128 v[76:79], v150 offset:57344
	v_mov_b32_e32 v80, v104
	v_mov_b32_e32 v81, v105
	v_mov_b32_e32 v82, v102
	v_mov_b32_e32 v83, v103
	s_waitcnt lgkmcnt(1)
	v_mfma_f32_32x32x16_bf16 v[48:63], v[72:75], v[68:71], v[48:63]
	s_waitcnt lgkmcnt(0)
	v_mfma_f32_32x32x16_bf16 v[32:47], v[76:79], v[68:71], v[32:47]
	ds_read_b128 v[68:71], v153 offset:49152
	ds_read_b128 v[72:75], v153 offset:57344
	v_mov_b32_e32 v76, v112
	v_mov_b32_e32 v77, v113
	v_mov_b32_e32 v78, v108
	v_mov_b32_e32 v79, v109
	s_waitcnt lgkmcnt(1)
	v_mfma_f32_32x32x16_bf16 v[48:63], v[68:71], v[64:67], v[48:63]
	s_waitcnt lgkmcnt(0)
; #define SBAR() __builtin_amdgcn_sched_barrier(0)
; #define BIAS(P0, P1, j) do { if (MODE == 1) { SBAR(); if ((j) >= nA) na_bias(P0, P1, na, rs0 + (j) - nA, hi); SBAR(); } } while (0)
; template <int DQK> __device__ __forceinline__ void partialSM(f32x16& p0, f32x16& p1, float& m_reg, float& mn, float& alpha) {
;   constexpr float SCALE = (DQK == 96) ? 0.10206207261596577f : 0.125f;
;   constexpr float C = SCALE * 1.4426950408889634f;
;   float pmax = p0[0];
; #pragma unroll
;   for (int r = 1; r < 16; ++r) pmax = fmaxf(pmax, p0[r]);
; #pragma unroll
;   for (int r = 0; r < 16; ++r) pmax = fmaxf(pmax, p1[r]);
;   { auto rr = __builtin_amdgcn_permlane32_swap(__float_as_uint(pmax), __float_as_uint(pmax), false, false);
;     pmax = fmaxf(__uint_as_float(rr[0]), __uint_as_float(rr[1])); }
;   if (__builtin_expect(__all(pmax - m_reg <= THR / SCALE), 1)) { mn = m_reg; alpha = 1.f; }
;   else { mn = fmaxf(m_reg, pmax); alpha = __builtin_amdgcn_exp2f((m_reg - mn) * C); m_reg = mn; }
;   float mnC = -mn * C;
; #pragma unroll
;   for (int r = 0; r < 16; ++r) p0[r] = fmaf(p0[r], C, mnC);
; #pragma unroll
;   for (int r = 0; r < 16; ++r) p1[r] = fmaf(p1[r], C, mnC);
; #pragma unroll
;   for (int r = 0; r < 16; ++r) p0[r] = __builtin_amdgcn_exp2f(p0[r]);
; }
; __device__ __forceinline__ void finishSM(f32x16& p0, f32x16& p1, float alpha, float& l_reg, bf16x8& pa0, bf16x8& pa1, bf16x8& pa2, bf16x8& pa3) {
; #pragma unroll
;   for (int r = 0; r < 16; ++r) p1[r] = __builtin_amdgcn_exp2f(p1[r]);
;   float ps = 0;
; #pragma unroll
;   for (int r = 0; r < 16; ++r) ps += p0[r];
; #pragma unroll
;   for (int r = 0; r < 16; ++r) ps += p1[r];
;   { auto rr = __builtin_amdgcn_permlane32_swap(__float_as_uint(ps), __float_as_uint(ps), false, false);
;     ps = __uint_as_float(rr[0]) + __uint_as_float(rr[1]); }
;   l_reg = l_reg * alpha + ps;
;     ...
;   PK4(p0, 0, pa0); PK4(p0, 8, pa1); PK4(p1, 0, pa2); PK4(p1, 8, pa3);
; template <int DQK, int MODE, int ldq, int ldk, int ldv> ...
;     ...
;   SBAR(); qkt<DQK>(pB0, pB1, K_lds + SHM_K, qr, r32, hi);
;   finishSM(pA0, pA1, alA, l_reg, pa0, pa1, pa2, pa3); SBAR();
;   pv_d0(o, vb0, pa0, pa1, pa2, pa3); BIAS(pB0, pB1, NT - 1); partialSM<DQK>(pB0, pB1, m_reg, mnB, alB);
	v_mfma_f32_32x32x16_bf16 v[32:47], v[72:75], v[64:67], v[32:47]
	v_add_f32_e32 v64, 0, v126
	v_add_f32_e32 v64, v160, v64
	v_add_f32_e32 v64, v127, v64
	v_add_f32_e32 v64, v161, v64
	v_add_f32_e32 v64, v158, v64
	v_add_f32_e32 v64, v162, v64
	v_add_f32_e32 v64, v159, v64
	v_add_f32_e32 v64, v163, v64
	v_add_f32_e32 v64, v118, v64
	v_add_f32_e32 v64, v121, v64
	v_add_f32_e32 v64, v119, v64
	v_add_f32_e32 v64, v122, v64
	v_mov_b32_e32 v74, v114
	v_add_f32_e32 v64, v120, v64
	v_mov_b32_e32 v75, v115
	v_add_f32_e32 v64, v123, v64
	v_add_f32_e32 v64, v124, v64
	v_add_f32_e32 v64, v125, v64
	v_add_f32_e32 v64, v74, v64
	v_add_f32_e32 v64, v75, v64
	v_add_f32_e32 v64, v76, v64
	v_add_f32_e32 v64, v77, v64
	v_add_f32_e32 v64, v78, v64
	v_add_f32_e32 v64, v79, v64
	v_add_f32_e32 v64, v80, v64
	v_add_f32_e32 v64, v81, v64
	v_add_f32_e32 v64, v82, v64
	v_add_f32_e32 v64, v83, v64
	v_add_f32_e32 v64, v84, v64
	v_add_f32_e32 v64, v85, v64
	v_add_f32_e32 v64, v86, v64
	v_add_f32_e32 v64, v87, v64
	v_add_f32_e32 v64, v88, v64
	v_add_f32_e32 v64, v89, v64
	v_mov_b32_e32 v65, v64
	v_cvt_pk_bf16_f32 v66, v126, v160
	v_cvt_pk_bf16_f32 v67, v127, v161
	v_cvt_pk_bf16_f32 v68, v158, v162
	v_cvt_pk_bf16_f32 v69, v159, v163
	s_nop 1
	v_permlane32_swap_b32_e32 v64, v65
	v_cvt_pk_bf16_f32 v70, v118, v121
	v_cvt_pk_bf16_f32 v71, v119, v122
	v_cvt_pk_bf16_f32 v72, v120, v123
	v_cvt_pk_bf16_f32 v73, v124, v125
	v_cvt_pk_bf16_f32 v74, v74, v75
	v_cvt_pk_bf16_f32 v75, v76, v77
	v_cvt_pk_bf16_f32 v76, v78, v79
	v_cvt_pk_bf16_f32 v77, v80, v81
	v_cvt_pk_bf16_f32 v78, v82, v83
	v_cvt_pk_bf16_f32 v79, v84, v85
	v_cvt_pk_bf16_f32 v80, v86, v87
	v_cvt_pk_bf16_f32 v81, v88, v89
	s_nop 0
	ds_read_b64_tr_b16 v[82:83], v144 offset:0
	ds_read_b64_tr_b16 v[84:85], v144 offset:0x800
	ds_read_b64_tr_b16 v[86:87], v144 offset:0x1000
	ds_read_b64_tr_b16 v[88:89], v144 offset:0x1800
	ds_read_b64_tr_b16 v[90:91], v144 offset:0x2000
	ds_read_b64_tr_b16 v[92:93], v144 offset:0x2800
	ds_read_b64_tr_b16 v[94:95], v144 offset:0x3000
	ds_read_b64_tr_b16 v[96:97], v144 offset:0x3800
	s_waitcnt lgkmcnt(0)
	s_nop 0
	v_mfma_f32_32x32x16_bf16 v[0:15], v[66:69], v[82:85], v[0:15]
	ds_read_b64_tr_b16 v[82:83], v144 offset:0x200
	ds_read_b64_tr_b16 v[84:85], v144 offset:0xa00
	v_mfma_f32_32x32x16_bf16 v[0:15], v[70:73], v[86:89], v[0:15]
	ds_read_b64_tr_b16 v[86:87], v144 offset:0x1200
	ds_read_b64_tr_b16 v[88:89], v144 offset:0x1a00
	v_mfma_f32_32x32x16_bf16 v[0:15], v[74:77], v[90:93], v[0:15]
	ds_read_b64_tr_b16 v[90:91], v144 offset:0x2200
	ds_read_b64_tr_b16 v[92:93], v144 offset:0x2a00
	v_mfma_f32_32x32x16_bf16 v[0:15], v[78:81], v[94:97], v[0:15]
	ds_read_b64_tr_b16 v[94:95], v144 offset:0x3200
	ds_read_b64_tr_b16 v[96:97], v144 offset:0x3a00
	s_waitcnt lgkmcnt(0)
	v_mfma_f32_32x32x16_bf16 v[16:31], v[66:69], v[82:85], v[16:31]
	v_max_f32_e32 v66, v49, v49
	v_max_f32_e32 v67, v48, v48
	v_max_f32_e32 v66, v67, v66
	v_max3_f32 v66, v66, v50, v51
	v_max3_f32 v66, v66, v52, v53
	v_max3_f32 v66, v66, v54, v55
	v_max3_f32 v66, v66, v56, v57
	v_max3_f32 v66, v66, v58, v59
	v_max3_f32 v66, v66, v60, v61
	v_mfma_f32_32x32x16_bf16 v[16:31], v[70:73], v[86:89], v[16:31]
	v_max3_f32 v66, v66, v62, v63
	v_max3_f32 v66, v66, v32, v33
	v_max3_f32 v66, v66, v34, v35
	v_max3_f32 v66, v66, v36, v37
	v_max3_f32 v66, v66, v38, v39
	v_max3_f32 v66, v66, v40, v41
	v_max3_f32 v66, v66, v42, v43
	v_max3_f32 v66, v66, v44, v45
	v_mfma_f32_32x32x16_bf16 v[16:31], v[74:77], v[90:93], v[16:31]
	v_max3_f32 v66, v66, v46, v47
	v_mov_b32_e32 v67, v66
	s_nop 1
	v_permlane32_swap_b32_e32 v66, v67
	v_max_f32_e32 v67, v67, v67
	v_max_f32_e32 v66, v66, v66
	v_max_f32_e32 v66, v66, v67
	v_sub_f32_e32 v67, v66, v116
	v_cmp_ge_f32_e32 vcc, s80, v67
	v_max_f32_e32 v67, v116, v116
	v_max_f32_e32 v67, v67, v66
	v_mfma_f32_32x32x16_bf16 v[16:31], v[78:81], v[94:97], v[16:31]
	v_sub_f32_e32 v66, v116, v67
	v_mul_f32_e32 v66, 0x3f800000, v66
	v_exp_f32_e32 v66, v66
	s_cmp_eq_u64 vcc, exec
	s_cselect_b64 s[0:1], -1, 0
	v_cndmask_b32_e64 v66, v66, 1.0, s[0:1]
	v_cmp_gt_f32_e32 vcc, 1.0, v66
	s_barrier
	s_cbranch_vccz .LBB0_316
	s_and_saveexec_b64 s[10:11], s[4:5]
	ds_write_b32 v141, v66 offset:128
	s_or_b64 exec, exec, s[10:11]
	s_waitcnt lgkmcnt(0)
	ds_read_b128 v[68:71], v129 offset:224
	ds_read_b128 v[72:75], v129 offset:192
	ds_read_b128 v[76:79], v129 offset:160
	ds_read_b128 v[80:83], v129 offset:128
	s_waitcnt lgkmcnt(3)
	v_pk_mul_f32 v[14:15], v[14:15], v[70:71]
	s_waitcnt lgkmcnt(2)
	v_pk_mul_f32 v[10:11], v[10:11], v[74:75]
	s_waitcnt lgkmcnt(1)
	v_pk_mul_f32 v[6:7], v[6:7], v[78:79]
	s_waitcnt lgkmcnt(0)
	v_pk_mul_f32 v[2:3], v[2:3], v[82:83]
	v_pk_mul_f32 v[12:13], v[12:13], v[68:69]
	v_pk_mul_f32 v[8:9], v[8:9], v[72:73]
	v_pk_mul_f32 v[4:5], v[4:5], v[76:77]
	v_pk_mul_f32 v[0:1], v[0:1], v[80:81]
	v_pk_mul_f32 v[30:31], v[30:31], v[70:71]
	v_pk_mul_f32 v[26:27], v[26:27], v[74:75]
	v_pk_mul_f32 v[22:23], v[22:23], v[78:79]
	v_pk_mul_f32 v[18:19], v[18:19], v[82:83]
	v_pk_mul_f32 v[28:29], v[28:29], v[68:69]
	v_pk_mul_f32 v[24:25], v[24:25], v[72:73]
	v_pk_mul_f32 v[20:21], v[20:21], v[76:77]
	v_pk_mul_f32 v[16:17], v[16:17], v[80:81]
